# on top of early-stop engines: removed the 16 back-to-back s_setprio 0 / s_setprio 1 pairs between the two 16-MFMA clusters of each K-loop super-phase
# speedup vs baseline: 1.0122x; 1.0122x over previous
.LBB0_222:
	s_waitcnt lgkmcnt(0)
	ds_read_b128 v[50:53], v188
	ds_read_b128 v[54:57], v188 offset:1024
	ds_read_b128 v[58:61], v188 offset:2048
	ds_read_b128 v[62:65], v188 offset:3072
	ds_read_b128 v[174:177], v189
	ds_read_b128 v[178:181], v189 offset:1024
	ds_read_b128 v[182:185], v189 offset:2048
	ds_read_b128 v[194:197], v189 offset:3072
	s_add_u32 s0, s6, 0xfffc0080
	s_addc_u32 s1, s7, -1
	s_cmp_eq_u32 s18, 12
	s_cselect_b32 s1, s2, s1
	s_cselect_b32 s0, s3, s0
	s_cselect_b32 s9, s11, s15
	s_cselect_b32 s8, s12, s13
	v_lshl_add_u64 v[230:231], s[6:7], 0, v[166:167]
	s_add_i32 m0, s21, 0xc000
	ds_read_b128 v[198:201], v190
	ds_read_b128 v[202:205], v190 offset:1024
	ds_read_b128 v[206:209], v190 offset:2048
	ds_read_b128 v[210:213], v190 offset:3072
	ds_read_b128 v[214:217], v190 offset:4096
	ds_read_b128 v[218:221], v190 offset:5120
	ds_read_b128 v[222:225], v190 offset:6144
	ds_read_b128 v[226:229], v190 offset:7168
	global_load_lds_dwordx4 v[230:231], off
	v_lshl_add_u64 v[230:231], s[6:7], 0, v[168:169]
	s_add_i32 m0, s21, 0xe000
	s_nop 0
	global_load_lds_dwordx4 v[230:231], off
	s_waitcnt vmcnt(8)
	s_waitcnt lgkmcnt(0)
	s_barrier
	s_setprio 1
	s_waitcnt lgkmcnt(0)
	v_mfma_f32_16x16x32_bf16 v[142:145], v[50:53], v[198:201], v[142:145]
	v_mfma_f32_16x16x32_bf16 v[138:141], v[58:61], v[198:201], v[138:141]
	v_mfma_f32_16x16x32_bf16 v[126:129], v[50:53], v[206:209], v[126:129]
	v_mfma_f32_16x16x32_bf16 v[122:125], v[58:61], v[206:209], v[122:125]
	v_mfma_f32_16x16x32_bf16 v[110:113], v[50:53], v[214:217], v[110:113]
	v_mfma_f32_16x16x32_bf16 v[106:109], v[58:61], v[214:217], v[106:109]
	v_mfma_f32_16x16x32_bf16 v[94:97], v[50:53], v[222:225], v[94:97]
	v_mfma_f32_16x16x32_bf16 v[90:93], v[58:61], v[222:225], v[90:93]
	v_mfma_f32_16x16x32_bf16 v[142:145], v[54:57], v[202:205], v[142:145]
	v_mfma_f32_16x16x32_bf16 v[138:141], v[62:65], v[202:205], v[138:141]
	v_mfma_f32_16x16x32_bf16 v[126:129], v[54:57], v[210:213], v[126:129]
	v_mfma_f32_16x16x32_bf16 v[122:125], v[62:65], v[210:213], v[122:125]
	v_mfma_f32_16x16x32_bf16 v[110:113], v[54:57], v[218:221], v[110:113]
	v_mfma_f32_16x16x32_bf16 v[106:109], v[62:65], v[218:221], v[106:109]
	v_mfma_f32_16x16x32_bf16 v[94:97], v[54:57], v[226:229], v[94:97]
	v_mfma_f32_16x16x32_bf16 v[90:93], v[62:65], v[226:229], v[90:93]
	v_mfma_f32_16x16x32_bf16 v[134:137], v[174:177], v[198:201], v[134:137]
	v_mfma_f32_16x16x32_bf16 v[130:133], v[182:185], v[198:201], v[130:133]
	v_mfma_f32_16x16x32_bf16 v[118:121], v[174:177], v[206:209], v[118:121]
	v_mfma_f32_16x16x32_bf16 v[114:117], v[182:185], v[206:209], v[114:117]
	v_mfma_f32_16x16x32_bf16 v[102:105], v[174:177], v[214:217], v[102:105]
	v_mfma_f32_16x16x32_bf16 v[98:101], v[182:185], v[214:217], v[98:101]
	v_mfma_f32_16x16x32_bf16 v[86:89], v[174:177], v[222:225], v[86:89]
	v_mfma_f32_16x16x32_bf16 v[82:85], v[182:185], v[222:225], v[82:85]
	v_mfma_f32_16x16x32_bf16 v[134:137], v[178:181], v[202:205], v[134:137]
	v_mfma_f32_16x16x32_bf16 v[130:133], v[194:197], v[202:205], v[130:133]
	v_mfma_f32_16x16x32_bf16 v[118:121], v[178:181], v[210:213], v[118:121]
	v_mfma_f32_16x16x32_bf16 v[114:117], v[194:197], v[210:213], v[114:117]
	v_mfma_f32_16x16x32_bf16 v[102:105], v[178:181], v[218:221], v[102:105]
	v_mfma_f32_16x16x32_bf16 v[98:101], v[194:197], v[218:221], v[98:101]
	v_mfma_f32_16x16x32_bf16 v[86:89], v[178:181], v[226:229], v[86:89]
	v_mfma_f32_16x16x32_bf16 v[82:85], v[194:197], v[226:229], v[82:85]
	s_setprio 0
	s_barrier
	s_add_i32 s19, s77, s20
	v_lshl_add_u64 v[230:231], s[8:9], 0, v[154:155]
	s_mov_b32 m0, s19
	ds_read_b128 v[198:201], v190 offset:16384
	ds_read_b128 v[202:205], v190 offset:17408
	ds_read_b128 v[206:209], v190 offset:18432
	ds_read_b128 v[210:213], v190 offset:19456
	ds_read_b128 v[214:217], v190 offset:20480
	ds_read_b128 v[218:221], v190 offset:21504
	ds_read_b128 v[222:225], v190 offset:22528
	ds_read_b128 v[226:229], v190 offset:23552
	global_load_lds_dwordx4 v[230:231], off
	s_add_i32 m0, s19, 0x2000
	s_add_u32 s24, s8, 0x40000
	v_lshl_add_u64 v[232:233], s[8:9], 0, v[156:157]
	s_addc_u32 s25, s9, 0
	s_add_i32 s19, s96, s20
	global_load_lds_dwordx4 v[232:233], off
	v_lshl_add_u64 v[234:235], s[24:25], 0, v[154:155]
	s_mov_b32 m0, s19
	v_lshl_add_u64 v[236:237], s[0:1], 0, v[156:157]
	global_load_lds_dwordx4 v[234:235], off
	v_lshl_add_u64 v[234:235], s[24:25], 0, v[156:157]
	s_add_i32 m0, s19, 0x2000
	s_nop 0
	global_load_lds_dwordx4 v[234:235], off
	v_lshl_add_u64 v[234:235], s[0:1], 0, v[154:155]
	s_mov_b32 m0, s21
	s_nop 0
	global_load_lds_dwordx4 v[234:235], off
	s_mov_b32 m0, s22
	s_nop 0
	global_load_lds_dwordx4 v[236:237], off
	s_waitcnt vmcnt(8)
	s_waitcnt lgkmcnt(0)
	s_barrier
	s_setprio 1
	s_waitcnt lgkmcnt(0)
	v_mfma_f32_16x16x32_bf16 v[78:81], v[50:53], v[198:201], v[78:81]
	v_mfma_f32_16x16x32_bf16 v[74:77], v[58:61], v[198:201], v[74:77]
	v_mfma_f32_16x16x32_bf16 v[46:49], v[50:53], v[206:209], v[46:49]
	v_mfma_f32_16x16x32_bf16 v[42:45], v[58:61], v[206:209], v[42:45]
	v_mfma_f32_16x16x32_bf16 v[30:33], v[50:53], v[214:217], v[30:33]
	v_mfma_f32_16x16x32_bf16 v[26:29], v[58:61], v[214:217], v[26:29]
	v_mfma_f32_16x16x32_bf16 v[14:17], v[50:53], v[222:225], v[14:17]
	v_mfma_f32_16x16x32_bf16 v[10:13], v[58:61], v[222:225], v[10:13]
	v_mfma_f32_16x16x32_bf16 v[78:81], v[54:57], v[202:205], v[78:81]
	v_mfma_f32_16x16x32_bf16 v[74:77], v[62:65], v[202:205], v[74:77]
	v_mfma_f32_16x16x32_bf16 v[46:49], v[54:57], v[210:213], v[46:49]
	v_mfma_f32_16x16x32_bf16 v[42:45], v[62:65], v[210:213], v[42:45]
	v_mfma_f32_16x16x32_bf16 v[30:33], v[54:57], v[218:221], v[30:33]
	v_mfma_f32_16x16x32_bf16 v[26:29], v[62:65], v[218:221], v[26:29]
	v_mfma_f32_16x16x32_bf16 v[14:17], v[54:57], v[226:229], v[14:17]
	v_mfma_f32_16x16x32_bf16 v[10:13], v[62:65], v[226:229], v[10:13]
	v_mfma_f32_16x16x32_bf16 v[38:41], v[174:177], v[206:209], v[38:41]
	v_mfma_f32_16x16x32_bf16 v[34:37], v[182:185], v[206:209], v[34:37]
	v_mfma_f32_16x16x32_bf16 v[22:25], v[174:177], v[214:217], v[22:25]
	v_mfma_f32_16x16x32_bf16 v[18:21], v[182:185], v[214:217], v[18:21]
	v_mfma_f32_16x16x32_bf16 v[6:9], v[174:177], v[222:225], v[6:9]
	v_mfma_f32_16x16x32_bf16 v[2:5], v[182:185], v[222:225], v[2:5]
	v_mfma_f32_16x16x32_bf16 v[50:53], v[174:177], v[198:201], v[70:73]
	v_mfma_f32_16x16x32_bf16 v[54:57], v[182:185], v[198:201], v[66:69]
	v_mfma_f32_16x16x32_bf16 v[38:41], v[178:181], v[210:213], v[38:41]
	v_mfma_f32_16x16x32_bf16 v[34:37], v[194:197], v[210:213], v[34:37]
	v_mfma_f32_16x16x32_bf16 v[22:25], v[178:181], v[218:221], v[22:25]
	v_mfma_f32_16x16x32_bf16 v[18:21], v[194:197], v[218:221], v[18:21]
	v_mfma_f32_16x16x32_bf16 v[6:9], v[178:181], v[226:229], v[6:9]
	v_mfma_f32_16x16x32_bf16 v[2:5], v[194:197], v[226:229], v[2:5]
	v_mfma_f32_16x16x32_bf16 v[50:53], v[178:181], v[202:205], v[50:53]
	v_mfma_f32_16x16x32_bf16 v[54:57], v[194:197], v[202:205], v[54:57]
	s_setprio 0
	s_barrier
	s_add_i32 s19, 0, 0x18000
	s_add_i32 s24, 0, 0x1c000
	v_add_u32_e32 v70, s19, v147
	v_add_u32_e32 v158, s24, v147
	ds_read_b128 v[58:61], v70
	ds_read_b128 v[62:65], v70 offset:1024
	ds_read_b128 v[66:69], v70 offset:2048
	ds_read_b128 v[70:73], v70 offset:3072
	ds_read_b128 v[174:177], v158
	ds_read_b128 v[178:181], v158 offset:1024
	ds_read_b128 v[182:185], v158 offset:2048
	ds_read_b128 v[194:197], v158 offset:3072
	s_add_u32 s0, s0, 0x40000
	s_addc_u32 s1, s1, 0
	s_mov_b32 m0, s23
	v_lshl_add_u64 v[238:239], s[0:1], 0, v[154:155]
	ds_read_b128 v[198:201], v190 offset:32768
	ds_read_b128 v[202:205], v190 offset:33792
	ds_read_b128 v[206:209], v190 offset:34816
	ds_read_b128 v[210:213], v190 offset:35840
	ds_read_b128 v[214:217], v190 offset:36864
	ds_read_b128 v[218:221], v190 offset:37888
	ds_read_b128 v[222:225], v190 offset:38912
	ds_read_b128 v[226:229], v190 offset:39936
	global_load_lds_dwordx4 v[238:239], off
	v_lshl_add_u64 v[238:239], s[0:1], 0, v[156:157]
	s_mov_b32 m0, s55
	s_nop 0
	global_load_lds_dwordx4 v[238:239], off
	s_waitcnt vmcnt(8)
	s_waitcnt lgkmcnt(0)
	s_barrier
	s_setprio 1
	s_waitcnt lgkmcnt(0)
	v_mfma_f32_16x16x32_bf16 v[142:145], v[58:61], v[198:201], v[142:145]
	v_mfma_f32_16x16x32_bf16 v[138:141], v[66:69], v[198:201], v[138:141]
	v_mfma_f32_16x16x32_bf16 v[126:129], v[58:61], v[206:209], v[126:129]
	v_mfma_f32_16x16x32_bf16 v[122:125], v[66:69], v[206:209], v[122:125]
	v_mfma_f32_16x16x32_bf16 v[110:113], v[58:61], v[214:217], v[110:113]
	v_mfma_f32_16x16x32_bf16 v[106:109], v[66:69], v[214:217], v[106:109]
	v_mfma_f32_16x16x32_bf16 v[94:97], v[58:61], v[222:225], v[94:97]
	v_mfma_f32_16x16x32_bf16 v[90:93], v[66:69], v[222:225], v[90:93]
	v_mfma_f32_16x16x32_bf16 v[142:145], v[62:65], v[202:205], v[142:145]
	v_mfma_f32_16x16x32_bf16 v[138:141], v[70:73], v[202:205], v[138:141]
	v_mfma_f32_16x16x32_bf16 v[126:129], v[62:65], v[210:213], v[126:129]
	v_mfma_f32_16x16x32_bf16 v[122:125], v[70:73], v[210:213], v[122:125]
	v_mfma_f32_16x16x32_bf16 v[110:113], v[62:65], v[218:221], v[110:113]
	v_mfma_f32_16x16x32_bf16 v[106:109], v[70:73], v[218:221], v[106:109]
	v_mfma_f32_16x16x32_bf16 v[94:97], v[62:65], v[226:229], v[94:97]
	v_mfma_f32_16x16x32_bf16 v[90:93], v[70:73], v[226:229], v[90:93]
	v_mfma_f32_16x16x32_bf16 v[134:137], v[174:177], v[198:201], v[134:137]
	v_mfma_f32_16x16x32_bf16 v[130:133], v[182:185], v[198:201], v[130:133]
	v_mfma_f32_16x16x32_bf16 v[118:121], v[174:177], v[206:209], v[118:121]
	v_mfma_f32_16x16x32_bf16 v[114:117], v[182:185], v[206:209], v[114:117]
	v_mfma_f32_16x16x32_bf16 v[102:105], v[174:177], v[214:217], v[102:105]
	v_mfma_f32_16x16x32_bf16 v[98:101], v[182:185], v[214:217], v[98:101]
	v_mfma_f32_16x16x32_bf16 v[86:89], v[174:177], v[222:225], v[86:89]
	v_mfma_f32_16x16x32_bf16 v[82:85], v[182:185], v[222:225], v[82:85]
	v_mfma_f32_16x16x32_bf16 v[134:137], v[178:181], v[202:205], v[134:137]
	v_mfma_f32_16x16x32_bf16 v[130:133], v[194:197], v[202:205], v[130:133]
	v_mfma_f32_16x16x32_bf16 v[118:121], v[178:181], v[210:213], v[118:121]
	v_mfma_f32_16x16x32_bf16 v[114:117], v[194:197], v[210:213], v[114:117]
	v_mfma_f32_16x16x32_bf16 v[102:105], v[178:181], v[218:221], v[102:105]
	v_mfma_f32_16x16x32_bf16 v[98:101], v[194:197], v[218:221], v[98:101]
	v_mfma_f32_16x16x32_bf16 v[86:89], v[178:181], v[226:229], v[86:89]
	v_mfma_f32_16x16x32_bf16 v[82:85], v[194:197], v[226:229], v[82:85]
	s_setprio 0
	s_barrier
	s_add_i32 s0, s19, s20
	v_lshl_add_u64 v[230:231], v[230:231], 0, s[84:85]
	s_mov_b32 m0, s0
	ds_read_b128 v[198:201], v190 offset:49152
	ds_read_b128 v[202:205], v190 offset:50176
	ds_read_b128 v[206:209], v190 offset:51200
	ds_read_b128 v[210:213], v190 offset:52224
	ds_read_b128 v[214:217], v190 offset:53248
	ds_read_b128 v[218:221], v190 offset:54272
	ds_read_b128 v[222:225], v190 offset:55296
	ds_read_b128 v[226:229], v190 offset:56320
	global_load_lds_dwordx4 v[230:231], off
	s_add_i32 m0, s0, 0x2000
	s_add_u32 s0, s8, 0x40080
	v_lshl_add_u64 v[230:231], v[232:233], 0, s[84:85]
	s_addc_u32 s1, s9, 0
	s_add_i32 s8, s24, s20
	global_load_lds_dwordx4 v[230:231], off
	v_lshl_add_u64 v[230:231], s[0:1], 0, v[154:155]
	s_mov_b32 m0, s8
	s_nop 0
	global_load_lds_dwordx4 v[230:231], off
	v_lshl_add_u64 v[230:231], s[0:1], 0, v[156:157]
	s_add_i32 m0, s8, 0x2000
	s_nop 0
	global_load_lds_dwordx4 v[230:231], off
	v_lshl_add_u64 v[230:231], v[234:235], 0, s[84:85]
	s_mov_b32 m0, s67
	s_nop 0
	global_load_lds_dwordx4 v[230:231], off
	v_lshl_add_u64 v[230:231], v[236:237], 0, s[84:85]
	s_mov_b32 m0, s72
	s_nop 0
	global_load_lds_dwordx4 v[230:231], off
	s_waitcnt vmcnt(8)
	s_waitcnt lgkmcnt(0)
	s_barrier
	s_setprio 1
	s_waitcnt lgkmcnt(0)
	v_mfma_f32_16x16x32_bf16 v[78:81], v[58:61], v[198:201], v[78:81]
	v_mfma_f32_16x16x32_bf16 v[74:77], v[66:69], v[198:201], v[74:77]
	v_mfma_f32_16x16x32_bf16 v[46:49], v[58:61], v[206:209], v[46:49]
	v_mfma_f32_16x16x32_bf16 v[42:45], v[66:69], v[206:209], v[42:45]
	v_mfma_f32_16x16x32_bf16 v[30:33], v[58:61], v[214:217], v[30:33]
	v_mfma_f32_16x16x32_bf16 v[26:29], v[66:69], v[214:217], v[26:29]
	v_mfma_f32_16x16x32_bf16 v[14:17], v[58:61], v[222:225], v[14:17]
	v_mfma_f32_16x16x32_bf16 v[10:13], v[66:69], v[222:225], v[10:13]
	v_mfma_f32_16x16x32_bf16 v[78:81], v[62:65], v[202:205], v[78:81]
	v_mfma_f32_16x16x32_bf16 v[74:77], v[70:73], v[202:205], v[74:77]
	v_mfma_f32_16x16x32_bf16 v[46:49], v[62:65], v[210:213], v[46:49]
	v_mfma_f32_16x16x32_bf16 v[42:45], v[70:73], v[210:213], v[42:45]
	v_mfma_f32_16x16x32_bf16 v[30:33], v[62:65], v[218:221], v[30:33]
	v_mfma_f32_16x16x32_bf16 v[26:29], v[70:73], v[218:221], v[26:29]
	v_mfma_f32_16x16x32_bf16 v[14:17], v[62:65], v[226:229], v[14:17]
	v_mfma_f32_16x16x32_bf16 v[10:13], v[70:73], v[226:229], v[10:13]
	v_mfma_f32_16x16x32_bf16 v[50:53], v[174:177], v[198:201], v[50:53]
	v_mfma_f32_16x16x32_bf16 v[70:73], v[178:181], v[202:205], v[50:53]
	v_mfma_f32_16x16x32_bf16 v[50:53], v[182:185], v[198:201], v[54:57]
	v_mfma_f32_16x16x32_bf16 v[38:41], v[174:177], v[206:209], v[38:41]
	v_mfma_f32_16x16x32_bf16 v[34:37], v[182:185], v[206:209], v[34:37]
	v_mfma_f32_16x16x32_bf16 v[22:25], v[174:177], v[214:217], v[22:25]
	v_mfma_f32_16x16x32_bf16 v[18:21], v[182:185], v[214:217], v[18:21]
	v_mfma_f32_16x16x32_bf16 v[6:9], v[174:177], v[222:225], v[6:9]
	v_mfma_f32_16x16x32_bf16 v[2:5], v[182:185], v[222:225], v[2:5]
	v_mfma_f32_16x16x32_bf16 v[66:69], v[194:197], v[202:205], v[50:53]
	v_mfma_f32_16x16x32_bf16 v[38:41], v[178:181], v[210:213], v[38:41]
	v_mfma_f32_16x16x32_bf16 v[34:37], v[194:197], v[210:213], v[34:37]
	v_mfma_f32_16x16x32_bf16 v[22:25], v[178:181], v[218:221], v[22:25]
	v_mfma_f32_16x16x32_bf16 v[18:21], v[194:197], v[218:221], v[18:21]
	v_mfma_f32_16x16x32_bf16 v[6:9], v[178:181], v[226:229], v[6:9]
	v_mfma_f32_16x16x32_bf16 v[2:5], v[194:197], v[226:229], v[2:5]
	s_setprio 0
	s_barrier
	s_add_i32 s18, s18, 2
	s_add_u32 s6, s6, 0x100
	s_addc_u32 s7, s7, 0
	s_add_u32 s13, s13, 0x100
	s_addc_u32 s15, s15, 0
	s_cmp_gt_u32 s18, 13
	s_cbranch_scc0 .LBB0_222
	s_and_b64 vcc, exec, s[86:87]
	s_cbranch_vccz .LBB0_225
	s_barrier

.LBB0_1797:
	ds_read_b128 v[130:133], v157
	ds_read_b128 v[152:155], v157 offset:1024
	ds_read_b128 v[160:163], v157 offset:2048
	ds_read_b128 v[164:167], v157 offset:3072
	ds_read_b128 v[168:171], v158
	ds_read_b128 v[172:175], v158 offset:1024
	ds_read_b128 v[176:179], v158 offset:2048
	ds_read_b128 v[180:183], v158 offset:3072
	s_add_u32 s0, s66, 0xfffc0080
	s_addc_u32 s1, s67, -1
	s_cmp_eq_u32 s91, 12
	s_cselect_b32 s71, s59, s1
	s_cselect_b32 s70, s87, s0
	s_cselect_b32 s69, s57, s90
	s_cselect_b32 s68, s88, s89
	v_lshl_add_u64 v[216:217], s[66:67], 0, v[140:141]
	s_add_i32 m0, s73, 0xc000
	ds_read_b128 v[184:187], v159
	ds_read_b128 v[188:191], v159 offset:1024
	ds_read_b128 v[192:195], v159 offset:2048
	ds_read_b128 v[196:199], v159 offset:3072
	ds_read_b128 v[200:203], v159 offset:4096
	ds_read_b128 v[204:207], v159 offset:5120
	ds_read_b128 v[208:211], v159 offset:6144
	ds_read_b128 v[212:215], v159 offset:7168
	global_load_lds_dwordx4 v[216:217], off
	v_lshl_add_u64 v[216:217], s[66:67], 0, v[142:143]
	s_add_i32 m0, s73, 0xe000
	s_nop 0
	global_load_lds_dwordx4 v[216:217], off
	s_waitcnt vmcnt(8)
	s_waitcnt lgkmcnt(0)
	s_barrier
	s_setprio 1
	s_waitcnt lgkmcnt(0)
	v_mfma_f32_16x16x32_bf16 v[126:129], v[130:133], v[184:187], v[126:129]
	v_mfma_f32_16x16x32_bf16 v[122:125], v[160:163], v[184:187], v[122:125]
	v_mfma_f32_16x16x32_bf16 v[114:117], v[130:133], v[192:195], v[114:117]
	v_mfma_f32_16x16x32_bf16 v[106:109], v[160:163], v[192:195], v[106:109]
	v_mfma_f32_16x16x32_bf16 v[94:97], v[130:133], v[200:203], v[94:97]
	v_mfma_f32_16x16x32_bf16 v[90:93], v[160:163], v[200:203], v[90:93]
	v_mfma_f32_16x16x32_bf16 v[82:85], v[130:133], v[208:211], v[82:85]
	v_mfma_f32_16x16x32_bf16 v[74:77], v[160:163], v[208:211], v[74:77]
	v_mfma_f32_16x16x32_bf16 v[126:129], v[152:155], v[188:191], v[126:129]
	v_mfma_f32_16x16x32_bf16 v[122:125], v[164:167], v[188:191], v[122:125]
	v_mfma_f32_16x16x32_bf16 v[114:117], v[152:155], v[196:199], v[114:117]
	v_mfma_f32_16x16x32_bf16 v[106:109], v[164:167], v[196:199], v[106:109]
	v_mfma_f32_16x16x32_bf16 v[94:97], v[152:155], v[204:207], v[94:97]
	v_mfma_f32_16x16x32_bf16 v[90:93], v[164:167], v[204:207], v[90:93]
	v_mfma_f32_16x16x32_bf16 v[82:85], v[152:155], v[212:215], v[82:85]
	v_mfma_f32_16x16x32_bf16 v[74:77], v[164:167], v[212:215], v[74:77]
	v_mfma_f32_16x16x32_bf16 v[118:121], v[168:171], v[184:187], v[118:121]
	v_mfma_f32_16x16x32_bf16 v[110:113], v[176:179], v[184:187], v[110:113]
	v_mfma_f32_16x16x32_bf16 v[102:105], v[168:171], v[192:195], v[102:105]
	v_mfma_f32_16x16x32_bf16 v[98:101], v[176:179], v[192:195], v[98:101]
	v_mfma_f32_16x16x32_bf16 v[86:89], v[168:171], v[200:203], v[86:89]
	v_mfma_f32_16x16x32_bf16 v[78:81], v[176:179], v[200:203], v[78:81]
	v_mfma_f32_16x16x32_bf16 v[70:73], v[168:171], v[208:211], v[70:73]
	v_mfma_f32_16x16x32_bf16 v[66:69], v[176:179], v[208:211], v[66:69]
	v_mfma_f32_16x16x32_bf16 v[118:121], v[172:175], v[188:191], v[118:121]
	v_mfma_f32_16x16x32_bf16 v[110:113], v[180:183], v[188:191], v[110:113]
	v_mfma_f32_16x16x32_bf16 v[102:105], v[172:175], v[196:199], v[102:105]
	v_mfma_f32_16x16x32_bf16 v[98:101], v[180:183], v[196:199], v[98:101]
	v_mfma_f32_16x16x32_bf16 v[86:89], v[172:175], v[204:207], v[86:89]
	v_mfma_f32_16x16x32_bf16 v[78:81], v[180:183], v[204:207], v[78:81]
	v_mfma_f32_16x16x32_bf16 v[70:73], v[172:175], v[212:215], v[70:73]
	v_mfma_f32_16x16x32_bf16 v[66:69], v[180:183], v[212:215], v[66:69]
	s_setprio 0
	s_barrier
	s_add_i32 s0, s85, s43
	v_lshl_add_u64 v[216:217], s[68:69], 0, v[136:137]
	s_mov_b32 m0, s0
	ds_read_b128 v[184:187], v159 offset:16384
	ds_read_b128 v[188:191], v159 offset:17408
	ds_read_b128 v[192:195], v159 offset:18432
	ds_read_b128 v[196:199], v159 offset:19456
	ds_read_b128 v[200:203], v159 offset:20480
	ds_read_b128 v[204:207], v159 offset:21504
	ds_read_b128 v[208:211], v159 offset:22528
	ds_read_b128 v[212:215], v159 offset:23552
	global_load_lds_dwordx4 v[216:217], off
	s_add_i32 m0, s0, 0x2000
	s_add_u32 s0, s68, 0x40000
	v_lshl_add_u64 v[218:219], s[68:69], 0, v[138:139]
	s_addc_u32 s1, s69, 0
	s_add_i32 s2, s86, s43
	global_load_lds_dwordx4 v[218:219], off
	v_lshl_add_u64 v[220:221], s[0:1], 0, v[136:137]
	s_mov_b32 m0, s2
	v_lshl_add_u64 v[222:223], s[70:71], 0, v[138:139]
	global_load_lds_dwordx4 v[220:221], off
	v_lshl_add_u64 v[220:221], s[0:1], 0, v[138:139]
	s_add_i32 m0, s2, 0x2000
	s_nop 0
	global_load_lds_dwordx4 v[220:221], off
	v_lshl_add_u64 v[220:221], s[70:71], 0, v[136:137]
	s_mov_b32 m0, s73
	s_nop 0
	global_load_lds_dwordx4 v[220:221], off
	s_mov_b32 m0, s74
	s_nop 0
	global_load_lds_dwordx4 v[222:223], off
	s_waitcnt vmcnt(8)
	s_waitcnt lgkmcnt(0)
	s_barrier
	s_setprio 1
	s_waitcnt lgkmcnt(0)
	v_mfma_f32_16x16x32_bf16 v[62:65], v[130:133], v[184:187], v[62:65]
	v_mfma_f32_16x16x32_bf16 v[58:61], v[160:163], v[184:187], v[58:61]
	v_mfma_f32_16x16x32_bf16 v[46:49], v[130:133], v[192:195], v[46:49]
	v_mfma_f32_16x16x32_bf16 v[42:45], v[160:163], v[192:195], v[42:45]
	v_mfma_f32_16x16x32_bf16 v[30:33], v[130:133], v[200:203], v[30:33]
	v_mfma_f32_16x16x32_bf16 v[26:29], v[160:163], v[200:203], v[26:29]
	v_mfma_f32_16x16x32_bf16 v[14:17], v[130:133], v[208:211], v[14:17]
	v_mfma_f32_16x16x32_bf16 v[10:13], v[160:163], v[208:211], v[10:13]
	v_mfma_f32_16x16x32_bf16 v[62:65], v[152:155], v[188:191], v[62:65]
	v_mfma_f32_16x16x32_bf16 v[58:61], v[164:167], v[188:191], v[58:61]
	v_mfma_f32_16x16x32_bf16 v[46:49], v[152:155], v[196:199], v[46:49]
	v_mfma_f32_16x16x32_bf16 v[42:45], v[164:167], v[196:199], v[42:45]
	v_mfma_f32_16x16x32_bf16 v[30:33], v[152:155], v[204:207], v[30:33]
	v_mfma_f32_16x16x32_bf16 v[26:29], v[164:167], v[204:207], v[26:29]
	v_mfma_f32_16x16x32_bf16 v[14:17], v[152:155], v[212:215], v[14:17]
	v_mfma_f32_16x16x32_bf16 v[10:13], v[164:167], v[212:215], v[10:13]
	v_mfma_f32_16x16x32_bf16 v[54:57], v[168:171], v[184:187], v[54:57]
	v_mfma_f32_16x16x32_bf16 v[50:53], v[176:179], v[184:187], v[50:53]
	v_mfma_f32_16x16x32_bf16 v[38:41], v[168:171], v[192:195], v[38:41]
	v_mfma_f32_16x16x32_bf16 v[34:37], v[176:179], v[192:195], v[34:37]
	v_mfma_f32_16x16x32_bf16 v[22:25], v[168:171], v[200:203], v[22:25]
	v_mfma_f32_16x16x32_bf16 v[18:21], v[176:179], v[200:203], v[18:21]
	v_mfma_f32_16x16x32_bf16 v[6:9], v[168:171], v[208:211], v[6:9]
	v_mfma_f32_16x16x32_bf16 v[2:5], v[176:179], v[208:211], v[2:5]
	v_mfma_f32_16x16x32_bf16 v[54:57], v[172:175], v[188:191], v[54:57]
	v_mfma_f32_16x16x32_bf16 v[50:53], v[180:183], v[188:191], v[50:53]
	v_mfma_f32_16x16x32_bf16 v[38:41], v[172:175], v[196:199], v[38:41]
	v_mfma_f32_16x16x32_bf16 v[34:37], v[180:183], v[196:199], v[34:37]
	v_mfma_f32_16x16x32_bf16 v[22:25], v[172:175], v[204:207], v[22:25]
	v_mfma_f32_16x16x32_bf16 v[18:21], v[180:183], v[204:207], v[18:21]
	v_mfma_f32_16x16x32_bf16 v[6:9], v[172:175], v[212:215], v[6:9]
	v_mfma_f32_16x16x32_bf16 v[2:5], v[180:183], v[212:215], v[2:5]
	s_setprio 0
	s_barrier
	s_add_i32 s2, 0, 0x18000
	s_add_i32 s3, 0, 0x1c000
	v_add_u32_e32 v164, s2, v147
	v_add_u32_e32 v180, s3, v147
	ds_read_b128 v[130:133], v164
	ds_read_b128 v[152:155], v164 offset:1024
	ds_read_b128 v[160:163], v164 offset:2048
	ds_read_b128 v[164:167], v164 offset:3072
	ds_read_b128 v[168:171], v180
	ds_read_b128 v[172:175], v180 offset:1024
	ds_read_b128 v[176:179], v180 offset:2048
	ds_read_b128 v[180:183], v180 offset:3072
	s_add_u32 s0, s70, 0x40000
	s_addc_u32 s1, s71, 0
	s_mov_b32 m0, s75
	v_lshl_add_u64 v[224:225], s[0:1], 0, v[136:137]
	ds_read_b128 v[184:187], v159 offset:32768
	ds_read_b128 v[188:191], v159 offset:33792
	ds_read_b128 v[192:195], v159 offset:34816
	ds_read_b128 v[196:199], v159 offset:35840
	ds_read_b128 v[200:203], v159 offset:36864
	ds_read_b128 v[204:207], v159 offset:37888
	ds_read_b128 v[208:211], v159 offset:38912
	ds_read_b128 v[212:215], v159 offset:39936
	global_load_lds_dwordx4 v[224:225], off
	v_lshl_add_u64 v[224:225], s[0:1], 0, v[138:139]
	s_mov_b32 m0, s76
	s_nop 0
	global_load_lds_dwordx4 v[224:225], off
	s_waitcnt vmcnt(8)
	s_waitcnt lgkmcnt(0)
	s_barrier
	s_setprio 1
	s_waitcnt lgkmcnt(0)
	v_mfma_f32_16x16x32_bf16 v[126:129], v[130:133], v[184:187], v[126:129]
	v_mfma_f32_16x16x32_bf16 v[122:125], v[160:163], v[184:187], v[122:125]
	v_mfma_f32_16x16x32_bf16 v[114:117], v[130:133], v[192:195], v[114:117]
	v_mfma_f32_16x16x32_bf16 v[106:109], v[160:163], v[192:195], v[106:109]
	v_mfma_f32_16x16x32_bf16 v[94:97], v[130:133], v[200:203], v[94:97]
	v_mfma_f32_16x16x32_bf16 v[90:93], v[160:163], v[200:203], v[90:93]
	v_mfma_f32_16x16x32_bf16 v[82:85], v[130:133], v[208:211], v[82:85]
	v_mfma_f32_16x16x32_bf16 v[74:77], v[160:163], v[208:211], v[74:77]
	v_mfma_f32_16x16x32_bf16 v[126:129], v[152:155], v[188:191], v[126:129]
	v_mfma_f32_16x16x32_bf16 v[122:125], v[164:167], v[188:191], v[122:125]
	v_mfma_f32_16x16x32_bf16 v[114:117], v[152:155], v[196:199], v[114:117]
	v_mfma_f32_16x16x32_bf16 v[106:109], v[164:167], v[196:199], v[106:109]
	v_mfma_f32_16x16x32_bf16 v[94:97], v[152:155], v[204:207], v[94:97]
	v_mfma_f32_16x16x32_bf16 v[90:93], v[164:167], v[204:207], v[90:93]
	v_mfma_f32_16x16x32_bf16 v[82:85], v[152:155], v[212:215], v[82:85]
	v_mfma_f32_16x16x32_bf16 v[74:77], v[164:167], v[212:215], v[74:77]
	v_mfma_f32_16x16x32_bf16 v[118:121], v[168:171], v[184:187], v[118:121]
	v_mfma_f32_16x16x32_bf16 v[110:113], v[176:179], v[184:187], v[110:113]
	v_mfma_f32_16x16x32_bf16 v[102:105], v[168:171], v[192:195], v[102:105]
	v_mfma_f32_16x16x32_bf16 v[98:101], v[176:179], v[192:195], v[98:101]
	v_mfma_f32_16x16x32_bf16 v[86:89], v[168:171], v[200:203], v[86:89]
	v_mfma_f32_16x16x32_bf16 v[78:81], v[176:179], v[200:203], v[78:81]
	v_mfma_f32_16x16x32_bf16 v[70:73], v[168:171], v[208:211], v[70:73]
	v_mfma_f32_16x16x32_bf16 v[66:69], v[176:179], v[208:211], v[66:69]
	v_mfma_f32_16x16x32_bf16 v[118:121], v[172:175], v[188:191], v[118:121]
	v_mfma_f32_16x16x32_bf16 v[110:113], v[180:183], v[188:191], v[110:113]
	v_mfma_f32_16x16x32_bf16 v[102:105], v[172:175], v[196:199], v[102:105]
	v_mfma_f32_16x16x32_bf16 v[98:101], v[180:183], v[196:199], v[98:101]
	v_mfma_f32_16x16x32_bf16 v[86:89], v[172:175], v[204:207], v[86:89]
	v_mfma_f32_16x16x32_bf16 v[78:81], v[180:183], v[204:207], v[78:81]
	v_mfma_f32_16x16x32_bf16 v[70:73], v[172:175], v[212:215], v[70:73]
	v_mfma_f32_16x16x32_bf16 v[66:69], v[180:183], v[212:215], v[66:69]
	s_setprio 0
	s_barrier
	s_add_i32 s0, s2, s43
	v_lshl_add_u64 v[216:217], v[216:217], 0, s[52:53]
	s_mov_b32 m0, s0
	ds_read_b128 v[184:187], v159 offset:49152
	ds_read_b128 v[188:191], v159 offset:50176
	ds_read_b128 v[192:195], v159 offset:51200
	ds_read_b128 v[196:199], v159 offset:52224
	ds_read_b128 v[200:203], v159 offset:53248
	ds_read_b128 v[204:207], v159 offset:54272
	ds_read_b128 v[208:211], v159 offset:55296
	ds_read_b128 v[212:215], v159 offset:56320
	global_load_lds_dwordx4 v[216:217], off
	s_add_i32 m0, s0, 0x2000
	s_add_u32 s0, s68, 0x40080
	v_lshl_add_u64 v[216:217], v[218:219], 0, s[52:53]
	s_addc_u32 s1, s69, 0
	s_add_i32 s2, s3, s43
	global_load_lds_dwordx4 v[216:217], off
	v_lshl_add_u64 v[216:217], s[0:1], 0, v[136:137]
	s_mov_b32 m0, s2
	s_nop 0
	global_load_lds_dwordx4 v[216:217], off
	v_lshl_add_u64 v[216:217], s[0:1], 0, v[138:139]
	s_add_i32 m0, s2, 0x2000
	s_nop 0
	global_load_lds_dwordx4 v[216:217], off
	v_lshl_add_u64 v[216:217], v[220:221], 0, s[52:53]
	s_mov_b32 m0, s83
	s_nop 0
	global_load_lds_dwordx4 v[216:217], off
	v_lshl_add_u64 v[216:217], v[222:223], 0, s[52:53]
	s_mov_b32 m0, s84
	s_nop 0
	global_load_lds_dwordx4 v[216:217], off
	s_waitcnt vmcnt(8)
	s_waitcnt lgkmcnt(0)
	s_barrier
	s_setprio 1
	s_waitcnt lgkmcnt(0)
	v_mfma_f32_16x16x32_bf16 v[62:65], v[130:133], v[184:187], v[62:65]
	v_mfma_f32_16x16x32_bf16 v[58:61], v[160:163], v[184:187], v[58:61]
	v_mfma_f32_16x16x32_bf16 v[46:49], v[130:133], v[192:195], v[46:49]
	v_mfma_f32_16x16x32_bf16 v[42:45], v[160:163], v[192:195], v[42:45]
	v_mfma_f32_16x16x32_bf16 v[30:33], v[130:133], v[200:203], v[30:33]
	v_mfma_f32_16x16x32_bf16 v[26:29], v[160:163], v[200:203], v[26:29]
	v_mfma_f32_16x16x32_bf16 v[14:17], v[130:133], v[208:211], v[14:17]
	v_mfma_f32_16x16x32_bf16 v[10:13], v[160:163], v[208:211], v[10:13]
	v_mfma_f32_16x16x32_bf16 v[62:65], v[152:155], v[188:191], v[62:65]
	v_mfma_f32_16x16x32_bf16 v[58:61], v[164:167], v[188:191], v[58:61]
	v_mfma_f32_16x16x32_bf16 v[46:49], v[152:155], v[196:199], v[46:49]
	v_mfma_f32_16x16x32_bf16 v[42:45], v[164:167], v[196:199], v[42:45]
	v_mfma_f32_16x16x32_bf16 v[30:33], v[152:155], v[204:207], v[30:33]
	v_mfma_f32_16x16x32_bf16 v[26:29], v[164:167], v[204:207], v[26:29]
	v_mfma_f32_16x16x32_bf16 v[14:17], v[152:155], v[212:215], v[14:17]
	v_mfma_f32_16x16x32_bf16 v[10:13], v[164:167], v[212:215], v[10:13]
	v_mfma_f32_16x16x32_bf16 v[54:57], v[168:171], v[184:187], v[54:57]
	v_mfma_f32_16x16x32_bf16 v[50:53], v[176:179], v[184:187], v[50:53]
	v_mfma_f32_16x16x32_bf16 v[38:41], v[168:171], v[192:195], v[38:41]
	v_mfma_f32_16x16x32_bf16 v[34:37], v[176:179], v[192:195], v[34:37]
	v_mfma_f32_16x16x32_bf16 v[22:25], v[168:171], v[200:203], v[22:25]
	v_mfma_f32_16x16x32_bf16 v[18:21], v[176:179], v[200:203], v[18:21]
	v_mfma_f32_16x16x32_bf16 v[6:9], v[168:171], v[208:211], v[6:9]
	v_mfma_f32_16x16x32_bf16 v[2:5], v[176:179], v[208:211], v[2:5]
	v_mfma_f32_16x16x32_bf16 v[54:57], v[172:175], v[188:191], v[54:57]
	v_mfma_f32_16x16x32_bf16 v[50:53], v[180:183], v[188:191], v[50:53]
	v_mfma_f32_16x16x32_bf16 v[38:41], v[172:175], v[196:199], v[38:41]
	v_mfma_f32_16x16x32_bf16 v[34:37], v[180:183], v[196:199], v[34:37]
	v_mfma_f32_16x16x32_bf16 v[22:25], v[172:175], v[204:207], v[22:25]
	v_mfma_f32_16x16x32_bf16 v[18:21], v[180:183], v[204:207], v[18:21]
	v_mfma_f32_16x16x32_bf16 v[6:9], v[172:175], v[212:215], v[6:9]
	v_mfma_f32_16x16x32_bf16 v[2:5], v[180:183], v[212:215], v[2:5]
	s_setprio 0
	s_barrier
	s_add_i32 s91, s91, 2
	s_add_u32 s66, s66, 0x100
	s_addc_u32 s67, s67, 0
	s_add_u32 s89, s89, 0x100
	s_addc_u32 s90, s90, 0
	s_cmp_gt_u32 s91, 13
	s_cbranch_scc0 .LBB0_1797
	s_and_b64 vcc, exec, s[54:55]
	s_cbranch_vccz .LBB0_1800
	s_barrier

.LBB0_2002:
	ds_read_b128 v[158:161], v154
	ds_read_b128 v[162:165], v154 offset:1024
	ds_read_b128 v[166:169], v154 offset:2048
	ds_read_b128 v[170:173], v154 offset:3072
	ds_read_b128 v[174:177], v155
	ds_read_b128 v[178:181], v155 offset:1024
	ds_read_b128 v[182:185], v155 offset:2048
	ds_read_b128 v[186:189], v155 offset:3072
	s_add_u32 s0, s62, 0xfffc0080
	s_addc_u32 s1, s63, -1
	s_cmp_eq_u32 s83, 12
	s_cselect_b32 s67, s55, s1
	s_cselect_b32 s66, s79, s0
	s_cselect_b32 s65, s53, s82
	s_cselect_b32 s64, s80, s81
	v_lshl_add_u64 v[150:151], s[62:63], 0, v[140:141]
	s_add_i32 m0, s61, 0xc000
	ds_read_b128 v[190:193], v156
	ds_read_b128 v[194:197], v156 offset:1024
	ds_read_b128 v[198:201], v156 offset:2048
	ds_read_b128 v[202:205], v156 offset:3072
	ds_read_b128 v[206:209], v156 offset:4096
	ds_read_b128 v[210:213], v156 offset:5120
	ds_read_b128 v[214:217], v156 offset:6144
	ds_read_b128 v[218:221], v156 offset:7168
	global_load_lds_dwordx4 v[150:151], off
	v_lshl_add_u64 v[150:151], s[62:63], 0, v[142:143]
	s_add_i32 m0, s61, 0xe000
	s_nop 0
	global_load_lds_dwordx4 v[150:151], off
	s_waitcnt vmcnt(8)
	s_waitcnt lgkmcnt(0)
	s_barrier
	s_setprio 1
	s_waitcnt lgkmcnt(0)
	v_mfma_f32_16x16x32_bf16 v[126:129], v[158:161], v[190:193], v[126:129]
	v_mfma_f32_16x16x32_bf16 v[122:125], v[166:169], v[190:193], v[122:125]
	v_mfma_f32_16x16x32_bf16 v[110:113], v[158:161], v[198:201], v[110:113]
	v_mfma_f32_16x16x32_bf16 v[106:109], v[166:169], v[198:201], v[106:109]
	v_mfma_f32_16x16x32_bf16 v[94:97], v[158:161], v[206:209], v[94:97]
	v_mfma_f32_16x16x32_bf16 v[90:93], v[166:169], v[206:209], v[90:93]
	v_mfma_f32_16x16x32_bf16 v[78:81], v[158:161], v[214:217], v[78:81]
	v_mfma_f32_16x16x32_bf16 v[74:77], v[166:169], v[214:217], v[74:77]
	v_mfma_f32_16x16x32_bf16 v[126:129], v[162:165], v[194:197], v[126:129]
	v_mfma_f32_16x16x32_bf16 v[122:125], v[170:173], v[194:197], v[122:125]
	v_mfma_f32_16x16x32_bf16 v[110:113], v[162:165], v[202:205], v[110:113]
	v_mfma_f32_16x16x32_bf16 v[106:109], v[170:173], v[202:205], v[106:109]
	v_mfma_f32_16x16x32_bf16 v[94:97], v[162:165], v[210:213], v[94:97]
	v_mfma_f32_16x16x32_bf16 v[90:93], v[170:173], v[210:213], v[90:93]
	v_mfma_f32_16x16x32_bf16 v[78:81], v[162:165], v[218:221], v[78:81]
	v_mfma_f32_16x16x32_bf16 v[74:77], v[170:173], v[218:221], v[74:77]
	v_mfma_f32_16x16x32_bf16 v[118:121], v[174:177], v[190:193], v[118:121]
	v_mfma_f32_16x16x32_bf16 v[114:117], v[182:185], v[190:193], v[114:117]
	v_mfma_f32_16x16x32_bf16 v[102:105], v[174:177], v[198:201], v[102:105]
	v_mfma_f32_16x16x32_bf16 v[98:101], v[182:185], v[198:201], v[98:101]
	v_mfma_f32_16x16x32_bf16 v[86:89], v[174:177], v[206:209], v[86:89]
	v_mfma_f32_16x16x32_bf16 v[82:85], v[182:185], v[206:209], v[82:85]
	v_mfma_f32_16x16x32_bf16 v[70:73], v[174:177], v[214:217], v[70:73]
	v_mfma_f32_16x16x32_bf16 v[66:69], v[182:185], v[214:217], v[66:69]
	v_mfma_f32_16x16x32_bf16 v[118:121], v[178:181], v[194:197], v[118:121]
	v_mfma_f32_16x16x32_bf16 v[114:117], v[186:189], v[194:197], v[114:117]
	v_mfma_f32_16x16x32_bf16 v[102:105], v[178:181], v[202:205], v[102:105]
	v_mfma_f32_16x16x32_bf16 v[98:101], v[186:189], v[202:205], v[98:101]
	v_mfma_f32_16x16x32_bf16 v[86:89], v[178:181], v[210:213], v[86:89]
	v_mfma_f32_16x16x32_bf16 v[82:85], v[186:189], v[210:213], v[82:85]
	v_mfma_f32_16x16x32_bf16 v[70:73], v[178:181], v[218:221], v[70:73]
	v_mfma_f32_16x16x32_bf16 v[66:69], v[186:189], v[218:221], v[66:69]
	s_setprio 0
	s_barrier
	s_add_i32 s0, s76, s68
	v_lshl_add_u64 v[150:151], s[64:65], 0, v[134:135]
	s_mov_b32 m0, s0
	ds_read_b128 v[190:193], v156 offset:16384
	ds_read_b128 v[194:197], v156 offset:17408
	ds_read_b128 v[198:201], v156 offset:18432
	ds_read_b128 v[202:205], v156 offset:19456
	ds_read_b128 v[206:209], v156 offset:20480
	ds_read_b128 v[210:213], v156 offset:21504
	ds_read_b128 v[214:217], v156 offset:22528
	ds_read_b128 v[218:221], v156 offset:23552
	global_load_lds_dwordx4 v[150:151], off
	s_add_i32 m0, s0, 0x2000
	s_add_u32 s0, s64, 0x40000
	v_lshl_add_u64 v[222:223], s[64:65], 0, v[138:139]
	s_addc_u32 s1, s65, 0
	s_add_i32 s6, s77, s68
	global_load_lds_dwordx4 v[222:223], off
	v_lshl_add_u64 v[224:225], s[0:1], 0, v[134:135]
	s_mov_b32 m0, s6
	v_lshl_add_u64 v[226:227], s[66:67], 0, v[136:137]
	global_load_lds_dwordx4 v[224:225], off
	v_lshl_add_u64 v[224:225], s[0:1], 0, v[138:139]
	s_add_i32 m0, s6, 0x2000
	s_nop 0
	global_load_lds_dwordx4 v[224:225], off
	v_lshl_add_u64 v[224:225], s[66:67], 0, v[132:133]
	s_mov_b32 m0, s61
	s_nop 0
	global_load_lds_dwordx4 v[224:225], off
	s_mov_b32 m0, s70
	s_nop 0
	global_load_lds_dwordx4 v[226:227], off
	s_waitcnt vmcnt(8)
	s_waitcnt lgkmcnt(0)
	s_barrier
	s_setprio 1
	s_waitcnt lgkmcnt(0)
	v_mfma_f32_16x16x32_bf16 v[62:65], v[158:161], v[190:193], v[62:65]
	v_mfma_f32_16x16x32_bf16 v[58:61], v[166:169], v[190:193], v[58:61]
	v_mfma_f32_16x16x32_bf16 v[46:49], v[158:161], v[198:201], v[46:49]
	v_mfma_f32_16x16x32_bf16 v[42:45], v[166:169], v[198:201], v[42:45]
	v_mfma_f32_16x16x32_bf16 v[30:33], v[158:161], v[206:209], v[30:33]
	v_mfma_f32_16x16x32_bf16 v[26:29], v[166:169], v[206:209], v[26:29]
	v_mfma_f32_16x16x32_bf16 v[14:17], v[158:161], v[214:217], v[14:17]
	v_mfma_f32_16x16x32_bf16 v[10:13], v[166:169], v[214:217], v[10:13]
	v_mfma_f32_16x16x32_bf16 v[62:65], v[162:165], v[194:197], v[62:65]
	v_mfma_f32_16x16x32_bf16 v[58:61], v[170:173], v[194:197], v[58:61]
	v_mfma_f32_16x16x32_bf16 v[46:49], v[162:165], v[202:205], v[46:49]
	v_mfma_f32_16x16x32_bf16 v[42:45], v[170:173], v[202:205], v[42:45]
	v_mfma_f32_16x16x32_bf16 v[30:33], v[162:165], v[210:213], v[30:33]
	v_mfma_f32_16x16x32_bf16 v[26:29], v[170:173], v[210:213], v[26:29]
	v_mfma_f32_16x16x32_bf16 v[14:17], v[162:165], v[218:221], v[14:17]
	v_mfma_f32_16x16x32_bf16 v[10:13], v[170:173], v[218:221], v[10:13]
	v_mfma_f32_16x16x32_bf16 v[54:57], v[174:177], v[190:193], v[54:57]
	v_mfma_f32_16x16x32_bf16 v[50:53], v[182:185], v[190:193], v[50:53]
	v_mfma_f32_16x16x32_bf16 v[38:41], v[174:177], v[198:201], v[38:41]
	v_mfma_f32_16x16x32_bf16 v[34:37], v[182:185], v[198:201], v[34:37]
	v_mfma_f32_16x16x32_bf16 v[22:25], v[174:177], v[206:209], v[22:25]
	v_mfma_f32_16x16x32_bf16 v[18:21], v[182:185], v[206:209], v[18:21]
	v_mfma_f32_16x16x32_bf16 v[6:9], v[174:177], v[214:217], v[6:9]
	v_mfma_f32_16x16x32_bf16 v[2:5], v[182:185], v[214:217], v[2:5]
	v_mfma_f32_16x16x32_bf16 v[54:57], v[178:181], v[194:197], v[54:57]
	v_mfma_f32_16x16x32_bf16 v[50:53], v[186:189], v[194:197], v[50:53]
	v_mfma_f32_16x16x32_bf16 v[38:41], v[178:181], v[202:205], v[38:41]
	v_mfma_f32_16x16x32_bf16 v[34:37], v[186:189], v[202:205], v[34:37]
	v_mfma_f32_16x16x32_bf16 v[22:25], v[178:181], v[210:213], v[22:25]
	v_mfma_f32_16x16x32_bf16 v[18:21], v[186:189], v[210:213], v[18:21]
	v_mfma_f32_16x16x32_bf16 v[6:9], v[178:181], v[218:221], v[6:9]
	v_mfma_f32_16x16x32_bf16 v[2:5], v[186:189], v[218:221], v[2:5]
	s_setprio 0
	s_barrier
	s_add_i32 s6, 0, 0x18000
	v_add_u32_e32 v157, s6, v152
	s_add_i32 s7, 0, 0x1c000
	ds_read_b128 v[158:161], v157
	ds_read_b128 v[162:165], v157 offset:1024
	ds_read_b128 v[166:169], v157 offset:2048
	ds_read_b128 v[170:173], v157 offset:3072
	v_add_u32_e32 v157, s7, v152
	ds_read_b128 v[174:177], v157
	ds_read_b128 v[178:181], v157 offset:1024
	ds_read_b128 v[182:185], v157 offset:2048
	ds_read_b128 v[186:189], v157 offset:3072
	s_add_u32 s0, s66, 0x40000
	s_addc_u32 s1, s67, 0
	s_mov_b32 m0, s71
	v_lshl_add_u64 v[228:229], s[0:1], 0, v[132:133]
	ds_read_b128 v[190:193], v156 offset:32768
	ds_read_b128 v[194:197], v156 offset:33792
	ds_read_b128 v[198:201], v156 offset:34816
	ds_read_b128 v[202:205], v156 offset:35840
	ds_read_b128 v[206:209], v156 offset:36864
	ds_read_b128 v[210:213], v156 offset:37888
	ds_read_b128 v[214:217], v156 offset:38912
	ds_read_b128 v[218:221], v156 offset:39936
	global_load_lds_dwordx4 v[228:229], off
	v_lshl_add_u64 v[228:229], s[0:1], 0, v[136:137]
	s_mov_b32 m0, s72
	s_nop 0
	global_load_lds_dwordx4 v[228:229], off
	s_waitcnt vmcnt(8)
	s_waitcnt lgkmcnt(0)
	s_barrier
	s_setprio 1
	s_waitcnt lgkmcnt(0)
	v_mfma_f32_16x16x32_bf16 v[126:129], v[158:161], v[190:193], v[126:129]
	v_mfma_f32_16x16x32_bf16 v[122:125], v[166:169], v[190:193], v[122:125]
	v_mfma_f32_16x16x32_bf16 v[110:113], v[158:161], v[198:201], v[110:113]
	v_mfma_f32_16x16x32_bf16 v[106:109], v[166:169], v[198:201], v[106:109]
	v_mfma_f32_16x16x32_bf16 v[94:97], v[158:161], v[206:209], v[94:97]
	v_mfma_f32_16x16x32_bf16 v[90:93], v[166:169], v[206:209], v[90:93]
	v_mfma_f32_16x16x32_bf16 v[78:81], v[158:161], v[214:217], v[78:81]
	v_mfma_f32_16x16x32_bf16 v[74:77], v[166:169], v[214:217], v[74:77]
	v_mfma_f32_16x16x32_bf16 v[126:129], v[162:165], v[194:197], v[126:129]
	v_mfma_f32_16x16x32_bf16 v[122:125], v[170:173], v[194:197], v[122:125]
	v_mfma_f32_16x16x32_bf16 v[110:113], v[162:165], v[202:205], v[110:113]
	v_mfma_f32_16x16x32_bf16 v[106:109], v[170:173], v[202:205], v[106:109]
	v_mfma_f32_16x16x32_bf16 v[94:97], v[162:165], v[210:213], v[94:97]
	v_mfma_f32_16x16x32_bf16 v[90:93], v[170:173], v[210:213], v[90:93]
	v_mfma_f32_16x16x32_bf16 v[78:81], v[162:165], v[218:221], v[78:81]
	v_mfma_f32_16x16x32_bf16 v[74:77], v[170:173], v[218:221], v[74:77]
	v_mfma_f32_16x16x32_bf16 v[118:121], v[174:177], v[190:193], v[118:121]
	v_mfma_f32_16x16x32_bf16 v[114:117], v[182:185], v[190:193], v[114:117]
	v_mfma_f32_16x16x32_bf16 v[102:105], v[174:177], v[198:201], v[102:105]
	v_mfma_f32_16x16x32_bf16 v[98:101], v[182:185], v[198:201], v[98:101]
	v_mfma_f32_16x16x32_bf16 v[86:89], v[174:177], v[206:209], v[86:89]
	v_mfma_f32_16x16x32_bf16 v[82:85], v[182:185], v[206:209], v[82:85]
	v_mfma_f32_16x16x32_bf16 v[70:73], v[174:177], v[214:217], v[70:73]
	v_mfma_f32_16x16x32_bf16 v[66:69], v[182:185], v[214:217], v[66:69]
	v_mfma_f32_16x16x32_bf16 v[118:121], v[178:181], v[194:197], v[118:121]
	v_mfma_f32_16x16x32_bf16 v[114:117], v[186:189], v[194:197], v[114:117]
	v_mfma_f32_16x16x32_bf16 v[102:105], v[178:181], v[202:205], v[102:105]
	v_mfma_f32_16x16x32_bf16 v[98:101], v[186:189], v[202:205], v[98:101]
	v_mfma_f32_16x16x32_bf16 v[86:89], v[178:181], v[210:213], v[86:89]
	v_mfma_f32_16x16x32_bf16 v[82:85], v[186:189], v[210:213], v[82:85]
	v_mfma_f32_16x16x32_bf16 v[70:73], v[178:181], v[218:221], v[70:73]
	v_mfma_f32_16x16x32_bf16 v[66:69], v[186:189], v[218:221], v[66:69]
	s_setprio 0
	s_barrier
	s_add_i32 s0, s6, s68
	v_lshl_add_u64 v[150:151], v[150:151], 0, s[48:49]
	s_mov_b32 m0, s0
	ds_read_b128 v[190:193], v156 offset:49152
	ds_read_b128 v[194:197], v156 offset:50176
	ds_read_b128 v[198:201], v156 offset:51200
	ds_read_b128 v[202:205], v156 offset:52224
	ds_read_b128 v[206:209], v156 offset:53248
	ds_read_b128 v[210:213], v156 offset:54272
	ds_read_b128 v[214:217], v156 offset:55296
	ds_read_b128 v[218:221], v156 offset:56320
	global_load_lds_dwordx4 v[150:151], off
	s_add_i32 m0, s0, 0x2000
	s_add_u32 s0, s64, 0x40080
	v_lshl_add_u64 v[150:151], v[222:223], 0, s[48:49]
	s_addc_u32 s1, s65, 0
	s_add_i32 s6, s7, s68
	global_load_lds_dwordx4 v[150:151], off
	v_lshl_add_u64 v[150:151], s[0:1], 0, v[134:135]
	s_mov_b32 m0, s6
	s_nop 0
	global_load_lds_dwordx4 v[150:151], off
	v_lshl_add_u64 v[150:151], s[0:1], 0, v[138:139]
	s_add_i32 m0, s6, 0x2000
	s_nop 0
	global_load_lds_dwordx4 v[150:151], off
	v_lshl_add_u64 v[150:151], v[224:225], 0, s[48:49]
	s_mov_b32 m0, s74
	s_nop 0
	global_load_lds_dwordx4 v[150:151], off
	v_lshl_add_u64 v[150:151], v[226:227], 0, s[48:49]
	s_mov_b32 m0, s75
	s_nop 0
	global_load_lds_dwordx4 v[150:151], off
	s_waitcnt vmcnt(8)
	s_waitcnt lgkmcnt(0)
	s_barrier
	s_setprio 1
	s_waitcnt lgkmcnt(0)
	v_mfma_f32_16x16x32_bf16 v[62:65], v[158:161], v[190:193], v[62:65]
	v_mfma_f32_16x16x32_bf16 v[58:61], v[166:169], v[190:193], v[58:61]
	v_mfma_f32_16x16x32_bf16 v[46:49], v[158:161], v[198:201], v[46:49]
	v_mfma_f32_16x16x32_bf16 v[42:45], v[166:169], v[198:201], v[42:45]
	v_mfma_f32_16x16x32_bf16 v[30:33], v[158:161], v[206:209], v[30:33]
	v_mfma_f32_16x16x32_bf16 v[26:29], v[166:169], v[206:209], v[26:29]
	v_mfma_f32_16x16x32_bf16 v[14:17], v[158:161], v[214:217], v[14:17]
	v_mfma_f32_16x16x32_bf16 v[10:13], v[166:169], v[214:217], v[10:13]
	v_mfma_f32_16x16x32_bf16 v[62:65], v[162:165], v[194:197], v[62:65]
	v_mfma_f32_16x16x32_bf16 v[58:61], v[170:173], v[194:197], v[58:61]
	v_mfma_f32_16x16x32_bf16 v[46:49], v[162:165], v[202:205], v[46:49]
	v_mfma_f32_16x16x32_bf16 v[42:45], v[170:173], v[202:205], v[42:45]
	v_mfma_f32_16x16x32_bf16 v[30:33], v[162:165], v[210:213], v[30:33]
	v_mfma_f32_16x16x32_bf16 v[26:29], v[170:173], v[210:213], v[26:29]
	v_mfma_f32_16x16x32_bf16 v[14:17], v[162:165], v[218:221], v[14:17]
	v_mfma_f32_16x16x32_bf16 v[10:13], v[170:173], v[218:221], v[10:13]
	v_mfma_f32_16x16x32_bf16 v[54:57], v[174:177], v[190:193], v[54:57]
	v_mfma_f32_16x16x32_bf16 v[50:53], v[182:185], v[190:193], v[50:53]
	v_mfma_f32_16x16x32_bf16 v[38:41], v[174:177], v[198:201], v[38:41]
	v_mfma_f32_16x16x32_bf16 v[34:37], v[182:185], v[198:201], v[34:37]
	v_mfma_f32_16x16x32_bf16 v[22:25], v[174:177], v[206:209], v[22:25]
	v_mfma_f32_16x16x32_bf16 v[18:21], v[182:185], v[206:209], v[18:21]
	v_mfma_f32_16x16x32_bf16 v[6:9], v[174:177], v[214:217], v[6:9]
	v_mfma_f32_16x16x32_bf16 v[2:5], v[182:185], v[214:217], v[2:5]
	v_mfma_f32_16x16x32_bf16 v[54:57], v[178:181], v[194:197], v[54:57]
	v_mfma_f32_16x16x32_bf16 v[50:53], v[186:189], v[194:197], v[50:53]
	v_mfma_f32_16x16x32_bf16 v[38:41], v[178:181], v[202:205], v[38:41]
	v_mfma_f32_16x16x32_bf16 v[34:37], v[186:189], v[202:205], v[34:37]
	v_mfma_f32_16x16x32_bf16 v[22:25], v[178:181], v[210:213], v[22:25]
	v_mfma_f32_16x16x32_bf16 v[18:21], v[186:189], v[210:213], v[18:21]
	v_mfma_f32_16x16x32_bf16 v[6:9], v[178:181], v[218:221], v[6:9]
	v_mfma_f32_16x16x32_bf16 v[2:5], v[186:189], v[218:221], v[2:5]
	s_setprio 0
	s_barrier
	s_add_i32 s83, s83, 2
	s_add_u32 s62, s62, 0x100
	s_addc_u32 s63, s63, 0
	s_add_u32 s81, s81, 0x100
	s_addc_u32 s82, s82, 0
	s_cmp_gt_u32 s83, 13
	s_cbranch_scc0 .LBB0_2002
	s_and_b64 vcc, exec, s[50:51]
	s_cbranch_vccz .LBB0_2005
	s_barrier

.LBB0_2141:
	ds_read_b128 v[142:145], v151
	ds_read_b128 v[154:157], v151 offset:1024
	ds_read_b128 v[158:161], v151 offset:2048
	ds_read_b128 v[162:165], v151 offset:3072
	ds_read_b128 v[166:169], v152
	ds_read_b128 v[170:173], v152 offset:1024
	ds_read_b128 v[174:177], v152 offset:2048
	ds_read_b128 v[178:181], v152 offset:3072
	s_add_u32 s0, s6, 0xfff00080
	s_addc_u32 s1, s7, -1
	s_cmp_eq_u32 s59, 60
	s_cselect_b32 s29, s21, s1
	s_cselect_b32 s28, s55, s0
	s_cselect_b32 s27, s19, s58
	s_cselect_b32 s26, s56, s57
	v_lshl_add_u64 v[214:215], s[6:7], 0, v[134:135]
	s_add_i32 m0, s34, 0xc000
	ds_read_b128 v[182:185], v153
	ds_read_b128 v[186:189], v153 offset:1024
	ds_read_b128 v[190:193], v153 offset:2048
	ds_read_b128 v[194:197], v153 offset:3072
	ds_read_b128 v[198:201], v153 offset:4096
	ds_read_b128 v[202:205], v153 offset:5120
	ds_read_b128 v[206:209], v153 offset:6144
	ds_read_b128 v[210:213], v153 offset:7168
	global_load_lds_dwordx4 v[214:215], off
	v_lshl_add_u64 v[214:215], s[6:7], 0, v[136:137]
	s_add_i32 m0, s34, 0xe000
	s_nop 0
	global_load_lds_dwordx4 v[214:215], off
	s_waitcnt vmcnt(8)
	s_waitcnt lgkmcnt(0)
	s_barrier
	s_setprio 1
	s_waitcnt lgkmcnt(0)
	v_mfma_f32_16x16x32_bf16 v[124:127], v[142:145], v[182:185], v[124:127]
	v_mfma_f32_16x16x32_bf16 v[120:123], v[158:161], v[182:185], v[120:123]
	v_mfma_f32_16x16x32_bf16 v[112:115], v[142:145], v[190:193], v[112:115]
	v_mfma_f32_16x16x32_bf16 v[104:107], v[158:161], v[190:193], v[104:107]
	v_mfma_f32_16x16x32_bf16 v[92:95], v[142:145], v[198:201], v[92:95]
	v_mfma_f32_16x16x32_bf16 v[88:91], v[158:161], v[198:201], v[88:91]
	v_mfma_f32_16x16x32_bf16 v[80:83], v[142:145], v[206:209], v[80:83]
	v_mfma_f32_16x16x32_bf16 v[72:75], v[158:161], v[206:209], v[72:75]
	v_mfma_f32_16x16x32_bf16 v[124:127], v[154:157], v[186:189], v[124:127]
	v_mfma_f32_16x16x32_bf16 v[120:123], v[162:165], v[186:189], v[120:123]
	v_mfma_f32_16x16x32_bf16 v[112:115], v[154:157], v[194:197], v[112:115]
	v_mfma_f32_16x16x32_bf16 v[104:107], v[162:165], v[194:197], v[104:107]
	v_mfma_f32_16x16x32_bf16 v[92:95], v[154:157], v[202:205], v[92:95]
	v_mfma_f32_16x16x32_bf16 v[88:91], v[162:165], v[202:205], v[88:91]
	v_mfma_f32_16x16x32_bf16 v[80:83], v[154:157], v[210:213], v[80:83]
	v_mfma_f32_16x16x32_bf16 v[72:75], v[162:165], v[210:213], v[72:75]
	v_mfma_f32_16x16x32_bf16 v[116:119], v[166:169], v[182:185], v[116:119]
	v_mfma_f32_16x16x32_bf16 v[108:111], v[174:177], v[182:185], v[108:111]
	v_mfma_f32_16x16x32_bf16 v[100:103], v[166:169], v[190:193], v[100:103]
	v_mfma_f32_16x16x32_bf16 v[96:99], v[174:177], v[190:193], v[96:99]
	v_mfma_f32_16x16x32_bf16 v[84:87], v[166:169], v[198:201], v[84:87]
	v_mfma_f32_16x16x32_bf16 v[76:79], v[174:177], v[198:201], v[76:79]
	v_mfma_f32_16x16x32_bf16 v[68:71], v[166:169], v[206:209], v[68:71]
	v_mfma_f32_16x16x32_bf16 v[64:67], v[174:177], v[206:209], v[64:67]
	v_mfma_f32_16x16x32_bf16 v[116:119], v[170:173], v[186:189], v[116:119]
	v_mfma_f32_16x16x32_bf16 v[108:111], v[178:181], v[186:189], v[108:111]
	v_mfma_f32_16x16x32_bf16 v[100:103], v[170:173], v[194:197], v[100:103]
	v_mfma_f32_16x16x32_bf16 v[96:99], v[178:181], v[194:197], v[96:99]
	v_mfma_f32_16x16x32_bf16 v[84:87], v[170:173], v[202:205], v[84:87]
	v_mfma_f32_16x16x32_bf16 v[76:79], v[178:181], v[202:205], v[76:79]
	v_mfma_f32_16x16x32_bf16 v[68:71], v[170:173], v[210:213], v[68:71]
	v_mfma_f32_16x16x32_bf16 v[64:67], v[178:181], v[210:213], v[64:67]
	s_setprio 0
	s_barrier
	s_add_i32 s0, s52, s30
	v_lshl_add_u64 v[214:215], s[26:27], 0, v[130:131]
	s_mov_b32 m0, s0
	ds_read_b128 v[182:185], v153 offset:16384
	ds_read_b128 v[186:189], v153 offset:17408
	ds_read_b128 v[190:193], v153 offset:18432
	ds_read_b128 v[194:197], v153 offset:19456
	ds_read_b128 v[198:201], v153 offset:20480
	ds_read_b128 v[202:205], v153 offset:21504
	ds_read_b128 v[206:209], v153 offset:22528
	ds_read_b128 v[210:213], v153 offset:23552
	global_load_lds_dwordx4 v[214:215], off
	s_add_i32 m0, s0, 0x2000
	s_add_u32 s0, s26, 0x100000
	v_lshl_add_u64 v[216:217], s[26:27], 0, v[132:133]
	s_addc_u32 s1, s27, 0
	s_add_i32 s60, s53, s30
	global_load_lds_dwordx4 v[216:217], off
	v_lshl_add_u64 v[218:219], s[0:1], 0, v[130:131]
	s_mov_b32 m0, s60
	v_lshl_add_u64 v[220:221], s[28:29], 0, v[132:133]
	global_load_lds_dwordx4 v[218:219], off
	v_lshl_add_u64 v[218:219], s[0:1], 0, v[132:133]
	s_add_i32 m0, s60, 0x2000
	s_nop 0
	global_load_lds_dwordx4 v[218:219], off
	v_lshl_add_u64 v[218:219], s[28:29], 0, v[130:131]
	s_mov_b32 m0, s34
	s_nop 0
	global_load_lds_dwordx4 v[218:219], off
	s_mov_b32 m0, s35
	s_nop 0
	global_load_lds_dwordx4 v[220:221], off
	s_waitcnt vmcnt(8)
	s_waitcnt lgkmcnt(0)
	s_barrier
	s_setprio 1
	s_waitcnt lgkmcnt(0)
	v_mfma_f32_16x16x32_bf16 v[60:63], v[142:145], v[182:185], v[60:63]
	v_mfma_f32_16x16x32_bf16 v[56:59], v[158:161], v[182:185], v[56:59]
	v_mfma_f32_16x16x32_bf16 v[48:51], v[142:145], v[190:193], v[48:51]
	v_mfma_f32_16x16x32_bf16 v[40:43], v[158:161], v[190:193], v[40:43]
	v_mfma_f32_16x16x32_bf16 v[28:31], v[142:145], v[198:201], v[28:31]
	v_mfma_f32_16x16x32_bf16 v[24:27], v[158:161], v[198:201], v[24:27]
	v_mfma_f32_16x16x32_bf16 v[16:19], v[142:145], v[206:209], v[16:19]
	v_mfma_f32_16x16x32_bf16 v[8:11], v[158:161], v[206:209], v[8:11]
	v_mfma_f32_16x16x32_bf16 v[60:63], v[154:157], v[186:189], v[60:63]
	v_mfma_f32_16x16x32_bf16 v[56:59], v[162:165], v[186:189], v[56:59]
	v_mfma_f32_16x16x32_bf16 v[48:51], v[154:157], v[194:197], v[48:51]
	v_mfma_f32_16x16x32_bf16 v[40:43], v[162:165], v[194:197], v[40:43]
	v_mfma_f32_16x16x32_bf16 v[28:31], v[154:157], v[202:205], v[28:31]
	v_mfma_f32_16x16x32_bf16 v[24:27], v[162:165], v[202:205], v[24:27]
	v_mfma_f32_16x16x32_bf16 v[16:19], v[154:157], v[210:213], v[16:19]
	v_mfma_f32_16x16x32_bf16 v[8:11], v[162:165], v[210:213], v[8:11]
	v_mfma_f32_16x16x32_bf16 v[52:55], v[166:169], v[182:185], v[52:55]
	v_mfma_f32_16x16x32_bf16 v[44:47], v[174:177], v[182:185], v[44:47]
	v_mfma_f32_16x16x32_bf16 v[36:39], v[166:169], v[190:193], v[36:39]
	v_mfma_f32_16x16x32_bf16 v[32:35], v[174:177], v[190:193], v[32:35]
	v_mfma_f32_16x16x32_bf16 v[20:23], v[166:169], v[198:201], v[20:23]
	v_mfma_f32_16x16x32_bf16 v[12:15], v[174:177], v[198:201], v[12:15]
	v_mfma_f32_16x16x32_bf16 v[4:7], v[166:169], v[206:209], v[4:7]
	v_mfma_f32_16x16x32_bf16 v[0:3], v[174:177], v[206:209], v[0:3]
	v_mfma_f32_16x16x32_bf16 v[52:55], v[170:173], v[186:189], v[52:55]
	v_mfma_f32_16x16x32_bf16 v[44:47], v[178:181], v[186:189], v[44:47]
	v_mfma_f32_16x16x32_bf16 v[36:39], v[170:173], v[194:197], v[36:39]
	v_mfma_f32_16x16x32_bf16 v[32:35], v[178:181], v[194:197], v[32:35]
	v_mfma_f32_16x16x32_bf16 v[20:23], v[170:173], v[202:205], v[20:23]
	v_mfma_f32_16x16x32_bf16 v[12:15], v[178:181], v[202:205], v[12:15]
	v_mfma_f32_16x16x32_bf16 v[4:7], v[170:173], v[210:213], v[4:7]
	v_mfma_f32_16x16x32_bf16 v[0:3], v[178:181], v[210:213], v[0:3]
	s_setprio 0
	s_barrier
	s_add_i32 s60, 0, 0x18000
	s_add_i32 s61, 0, 0x1c000
	v_add_u32_e32 v162, s60, v147
	v_add_u32_e32 v178, s61, v147
	ds_read_b128 v[142:145], v162
	ds_read_b128 v[154:157], v162 offset:1024
	ds_read_b128 v[158:161], v162 offset:2048
	ds_read_b128 v[162:165], v162 offset:3072
	ds_read_b128 v[166:169], v178
	ds_read_b128 v[170:173], v178 offset:1024
	ds_read_b128 v[174:177], v178 offset:2048
	ds_read_b128 v[178:181], v178 offset:3072
	s_add_u32 s0, s28, 0x100000
	s_addc_u32 s1, s29, 0
	s_mov_b32 m0, s36
	v_lshl_add_u64 v[222:223], s[0:1], 0, v[130:131]
	ds_read_b128 v[182:185], v153 offset:32768
	ds_read_b128 v[186:189], v153 offset:33792
	ds_read_b128 v[190:193], v153 offset:34816
	ds_read_b128 v[194:197], v153 offset:35840
	ds_read_b128 v[198:201], v153 offset:36864
	ds_read_b128 v[202:205], v153 offset:37888
	ds_read_b128 v[206:209], v153 offset:38912
	ds_read_b128 v[210:213], v153 offset:39936
	global_load_lds_dwordx4 v[222:223], off
	v_lshl_add_u64 v[222:223], s[0:1], 0, v[132:133]
	s_mov_b32 m0, s37
	s_nop 0
	global_load_lds_dwordx4 v[222:223], off
	s_waitcnt vmcnt(8)
	s_waitcnt lgkmcnt(0)
	s_barrier
	s_setprio 1
	s_waitcnt lgkmcnt(0)
	v_mfma_f32_16x16x32_bf16 v[124:127], v[142:145], v[182:185], v[124:127]
	v_mfma_f32_16x16x32_bf16 v[120:123], v[158:161], v[182:185], v[120:123]
	v_mfma_f32_16x16x32_bf16 v[112:115], v[142:145], v[190:193], v[112:115]
	v_mfma_f32_16x16x32_bf16 v[104:107], v[158:161], v[190:193], v[104:107]
	v_mfma_f32_16x16x32_bf16 v[92:95], v[142:145], v[198:201], v[92:95]
	v_mfma_f32_16x16x32_bf16 v[88:91], v[158:161], v[198:201], v[88:91]
	v_mfma_f32_16x16x32_bf16 v[80:83], v[142:145], v[206:209], v[80:83]
	v_mfma_f32_16x16x32_bf16 v[72:75], v[158:161], v[206:209], v[72:75]
	v_mfma_f32_16x16x32_bf16 v[124:127], v[154:157], v[186:189], v[124:127]
	v_mfma_f32_16x16x32_bf16 v[120:123], v[162:165], v[186:189], v[120:123]
	v_mfma_f32_16x16x32_bf16 v[112:115], v[154:157], v[194:197], v[112:115]
	v_mfma_f32_16x16x32_bf16 v[104:107], v[162:165], v[194:197], v[104:107]
	v_mfma_f32_16x16x32_bf16 v[92:95], v[154:157], v[202:205], v[92:95]
	v_mfma_f32_16x16x32_bf16 v[88:91], v[162:165], v[202:205], v[88:91]
	v_mfma_f32_16x16x32_bf16 v[80:83], v[154:157], v[210:213], v[80:83]
	v_mfma_f32_16x16x32_bf16 v[72:75], v[162:165], v[210:213], v[72:75]
	v_mfma_f32_16x16x32_bf16 v[116:119], v[166:169], v[182:185], v[116:119]
	v_mfma_f32_16x16x32_bf16 v[108:111], v[174:177], v[182:185], v[108:111]
	v_mfma_f32_16x16x32_bf16 v[100:103], v[166:169], v[190:193], v[100:103]
	v_mfma_f32_16x16x32_bf16 v[96:99], v[174:177], v[190:193], v[96:99]
	v_mfma_f32_16x16x32_bf16 v[84:87], v[166:169], v[198:201], v[84:87]
	v_mfma_f32_16x16x32_bf16 v[76:79], v[174:177], v[198:201], v[76:79]
	v_mfma_f32_16x16x32_bf16 v[68:71], v[166:169], v[206:209], v[68:71]
	v_mfma_f32_16x16x32_bf16 v[64:67], v[174:177], v[206:209], v[64:67]
	v_mfma_f32_16x16x32_bf16 v[116:119], v[170:173], v[186:189], v[116:119]
	v_mfma_f32_16x16x32_bf16 v[108:111], v[178:181], v[186:189], v[108:111]
	v_mfma_f32_16x16x32_bf16 v[100:103], v[170:173], v[194:197], v[100:103]
	v_mfma_f32_16x16x32_bf16 v[96:99], v[178:181], v[194:197], v[96:99]
	v_mfma_f32_16x16x32_bf16 v[84:87], v[170:173], v[202:205], v[84:87]
	v_mfma_f32_16x16x32_bf16 v[76:79], v[178:181], v[202:205], v[76:79]
	v_mfma_f32_16x16x32_bf16 v[68:71], v[170:173], v[210:213], v[68:71]
	v_mfma_f32_16x16x32_bf16 v[64:67], v[178:181], v[210:213], v[64:67]
	s_setprio 0
	s_barrier
	s_add_i32 s0, s60, s30
	v_lshl_add_u64 v[214:215], v[214:215], 0, s[14:15]
	s_mov_b32 m0, s0
	ds_read_b128 v[182:185], v153 offset:49152
	ds_read_b128 v[186:189], v153 offset:50176
	ds_read_b128 v[190:193], v153 offset:51200
	ds_read_b128 v[194:197], v153 offset:52224
	ds_read_b128 v[198:201], v153 offset:53248
	ds_read_b128 v[202:205], v153 offset:54272
	ds_read_b128 v[206:209], v153 offset:55296
	ds_read_b128 v[210:213], v153 offset:56320
	global_load_lds_dwordx4 v[214:215], off
	s_add_i32 m0, s0, 0x2000
	s_add_u32 s0, s26, 0x100080
	v_lshl_add_u64 v[214:215], v[216:217], 0, s[14:15]
	s_addc_u32 s1, s27, 0
	s_add_i32 s26, s61, s30
	global_load_lds_dwordx4 v[214:215], off
	v_lshl_add_u64 v[214:215], s[0:1], 0, v[130:131]
	s_mov_b32 m0, s26
	s_nop 0
	global_load_lds_dwordx4 v[214:215], off
	v_lshl_add_u64 v[214:215], s[0:1], 0, v[132:133]
	s_add_i32 m0, s26, 0x2000
	s_nop 0
	global_load_lds_dwordx4 v[214:215], off
	v_lshl_add_u64 v[214:215], v[218:219], 0, s[14:15]
	s_mov_b32 m0, s49
	s_nop 0
	global_load_lds_dwordx4 v[214:215], off
	v_lshl_add_u64 v[214:215], v[220:221], 0, s[14:15]
	s_mov_b32 m0, s50
	s_nop 0
	global_load_lds_dwordx4 v[214:215], off
	s_waitcnt vmcnt(8)
	s_waitcnt lgkmcnt(0)
	s_barrier
	s_setprio 1
	s_waitcnt lgkmcnt(0)
	v_mfma_f32_16x16x32_bf16 v[60:63], v[142:145], v[182:185], v[60:63]
	v_mfma_f32_16x16x32_bf16 v[56:59], v[158:161], v[182:185], v[56:59]
	v_mfma_f32_16x16x32_bf16 v[48:51], v[142:145], v[190:193], v[48:51]
	v_mfma_f32_16x16x32_bf16 v[40:43], v[158:161], v[190:193], v[40:43]
	v_mfma_f32_16x16x32_bf16 v[28:31], v[142:145], v[198:201], v[28:31]
	v_mfma_f32_16x16x32_bf16 v[24:27], v[158:161], v[198:201], v[24:27]
	v_mfma_f32_16x16x32_bf16 v[16:19], v[142:145], v[206:209], v[16:19]
	v_mfma_f32_16x16x32_bf16 v[8:11], v[158:161], v[206:209], v[8:11]
	v_mfma_f32_16x16x32_bf16 v[60:63], v[154:157], v[186:189], v[60:63]
	v_mfma_f32_16x16x32_bf16 v[56:59], v[162:165], v[186:189], v[56:59]
	v_mfma_f32_16x16x32_bf16 v[48:51], v[154:157], v[194:197], v[48:51]
	v_mfma_f32_16x16x32_bf16 v[40:43], v[162:165], v[194:197], v[40:43]
	v_mfma_f32_16x16x32_bf16 v[28:31], v[154:157], v[202:205], v[28:31]
	v_mfma_f32_16x16x32_bf16 v[24:27], v[162:165], v[202:205], v[24:27]
	v_mfma_f32_16x16x32_bf16 v[16:19], v[154:157], v[210:213], v[16:19]
	v_mfma_f32_16x16x32_bf16 v[8:11], v[162:165], v[210:213], v[8:11]
	v_mfma_f32_16x16x32_bf16 v[52:55], v[166:169], v[182:185], v[52:55]
	v_mfma_f32_16x16x32_bf16 v[44:47], v[174:177], v[182:185], v[44:47]
	v_mfma_f32_16x16x32_bf16 v[36:39], v[166:169], v[190:193], v[36:39]
	v_mfma_f32_16x16x32_bf16 v[32:35], v[174:177], v[190:193], v[32:35]
	v_mfma_f32_16x16x32_bf16 v[20:23], v[166:169], v[198:201], v[20:23]
	v_mfma_f32_16x16x32_bf16 v[12:15], v[174:177], v[198:201], v[12:15]
	v_mfma_f32_16x16x32_bf16 v[4:7], v[166:169], v[206:209], v[4:7]
	v_mfma_f32_16x16x32_bf16 v[0:3], v[174:177], v[206:209], v[0:3]
	v_mfma_f32_16x16x32_bf16 v[52:55], v[170:173], v[186:189], v[52:55]
	v_mfma_f32_16x16x32_bf16 v[44:47], v[178:181], v[186:189], v[44:47]
	v_mfma_f32_16x16x32_bf16 v[36:39], v[170:173], v[194:197], v[36:39]
	v_mfma_f32_16x16x32_bf16 v[32:35], v[178:181], v[194:197], v[32:35]
	v_mfma_f32_16x16x32_bf16 v[20:23], v[170:173], v[202:205], v[20:23]
	v_mfma_f32_16x16x32_bf16 v[12:15], v[178:181], v[202:205], v[12:15]
	v_mfma_f32_16x16x32_bf16 v[4:7], v[170:173], v[210:213], v[4:7]
	v_mfma_f32_16x16x32_bf16 v[0:3], v[178:181], v[210:213], v[0:3]
	s_setprio 0
	s_barrier
	s_add_i32 s59, s59, 2
	s_add_u32 s6, s6, 0x100
	s_addc_u32 s7, s7, 0
	s_add_u32 s57, s57, 0x100
	s_addc_u32 s58, s58, 0
	s_cmp_gt_u32 s59, 61
	s_cbranch_scc0 .LBB0_2141
	s_and_b64 vcc, exec, s[16:17]
	s_cbranch_vccz .LBB0_2144
	s_barrier
